# adds: HGRN full-pass prologue S = d_j*S + U_j with the next segment's loads issued before the current one is consumed
# baseline (speedup 1.0000x reference)
.LBB0_332:
	global_load_dwordx4 v[58:61], v[34:35], off
	global_load_dword v62, v[36:37], off
	global_load_dword v63, v[38:39], off offset:-512
	global_load_dword v64, v[38:39], off offset:-960
	global_load_dword v98, v[38:39], off
	global_load_dword v65, v[38:39], off offset:-448
	global_load_dword v101, v[38:39], off offset:-384
	global_load_dword v103, v[38:39], off offset:-320
	global_load_dword v105, v[38:39], off offset:-256
	global_load_dword v99, v[38:39], off offset:512
	global_load_dword v106, v[38:39], off offset:64
	global_load_dword v108, v[38:39], off offset:128
	global_load_dword v110, v[38:39], off offset:192
	global_load_dword v112, v[38:39], off offset:256
	global_load_dword v114, v[38:39], off offset:320
	global_load_dword v107, v[38:39], off offset:576
	global_load_dword v109, v[38:39], off offset:640
	global_load_dword v111, v[38:39], off offset:704
	global_load_dword v113, v[38:39], off offset:768
	global_load_dword v115, v[38:39], off offset:832
	global_load_dword v117, v[38:39], off offset:896
	global_load_dword v100, v[38:39], off offset:-896
	global_load_dword v102, v[38:39], off offset:-832
	global_load_dword v104, v[38:39], off offset:-768
	global_load_dword v118, v[38:39], off offset:-704
	global_load_dword v120, v[38:39], off offset:-640
	global_load_dword v122, v[38:39], off offset:-576
	global_load_dword v119, v[38:39], off offset:-192
	global_load_dword v121, v[38:39], off offset:-128
	global_load_dword v123, v[38:39], off offset:-64
	global_load_dword v116, v[38:39], off offset:384
	global_load_dword v124, v[38:39], off offset:448
	global_load_dword v125, v[38:39], off offset:960
	s_mov_b64 s[10:11], 0x200
	v_lshl_add_u64 v[34:35], v[34:35], 0, s[10:11]
	v_lshl_add_u64 v[36:37], v[36:37], 0, s[94:95]
	v_lshl_add_u64 v[38:39], v[38:39], 0, s[94:95]
	s_cmp_eq_u32 s4, 1
	s_cbranch_scc1 .Lhgu_lastA
	global_load_dwordx4 v[196:199], v[34:35], off
	global_load_dword v200, v[36:37], off
	global_load_dword v201, v[38:39], off offset:-512
	global_load_dword v202, v[38:39], off offset:-960
	global_load_dword v204, v[38:39], off
	global_load_dword v203, v[38:39], off offset:-448
	global_load_dword v207, v[38:39], off offset:-384
	global_load_dword v209, v[38:39], off offset:-320
	global_load_dword v211, v[38:39], off offset:-256
	global_load_dword v205, v[38:39], off offset:512
	global_load_dword v212, v[38:39], off offset:64
	global_load_dword v214, v[38:39], off offset:128
	global_load_dword v216, v[38:39], off offset:192
	global_load_dword v218, v[38:39], off offset:256
	global_load_dword v220, v[38:39], off offset:320
	global_load_dword v213, v[38:39], off offset:576
	global_load_dword v215, v[38:39], off offset:640
	global_load_dword v217, v[38:39], off offset:704
	global_load_dword v219, v[38:39], off offset:768
	global_load_dword v221, v[38:39], off offset:832
	global_load_dword v223, v[38:39], off offset:896
	global_load_dword v206, v[38:39], off offset:-896
	global_load_dword v208, v[38:39], off offset:-832
	global_load_dword v210, v[38:39], off offset:-768
	global_load_dword v224, v[38:39], off offset:-704
	global_load_dword v226, v[38:39], off offset:-640
	global_load_dword v228, v[38:39], off offset:-576
	global_load_dword v225, v[38:39], off offset:-192
	global_load_dword v227, v[38:39], off offset:-128
	global_load_dword v229, v[38:39], off offset:-64
	global_load_dword v222, v[38:39], off offset:384
	global_load_dword v230, v[38:39], off offset:448
	global_load_dword v231, v[38:39], off offset:960
	v_lshl_add_u64 v[34:35], v[34:35], 0, s[10:11]
	v_lshl_add_u64 v[36:37], v[36:37], 0, s[94:95]
	v_lshl_add_u64 v[38:39], v[38:39], 0, s[94:95]
	s_waitcnt vmcnt(33)
	v_pk_fma_f32 v[2:3], v[2:3], v[58:59], v[62:63]
	v_pk_fma_f32 v[6:7], v[6:7], v[58:59], v[64:65]
	v_pk_fma_f32 v[4:5], v[4:5], v[60:61], v[98:99]
	v_pk_fma_f32 v[8:9], v[8:9], v[60:61], v[106:107]
	v_pk_fma_f32 v[12:13], v[12:13], v[60:61], v[108:109]
	v_pk_fma_f32 v[16:17], v[16:17], v[60:61], v[110:111]
	v_pk_fma_f32 v[20:21], v[20:21], v[60:61], v[112:113]
	v_pk_fma_f32 v[24:25], v[24:25], v[60:61], v[114:115]
	v_pk_fma_f32 v[10:11], v[10:11], v[58:59], v[100:101]
	v_pk_fma_f32 v[14:15], v[14:15], v[58:59], v[102:103]
	v_pk_fma_f32 v[18:19], v[18:19], v[58:59], v[104:105]
	v_pk_fma_f32 v[22:23], v[22:23], v[58:59], v[118:119]
	v_pk_fma_f32 v[26:27], v[26:27], v[58:59], v[120:121]
	v_pk_fma_f32 v[30:31], v[30:31], v[58:59], v[122:123]
	v_pk_fma_f32 v[28:29], v[28:29], v[60:61], v[116:117]
	v_pk_fma_f32 v[32:33], v[32:33], v[60:61], v[124:125]
	s_cmp_eq_u32 s4, 2
	s_cbranch_scc1 .Lhgu_lastB
	global_load_dwordx4 v[58:61], v[34:35], off
	global_load_dword v62, v[36:37], off
	global_load_dword v63, v[38:39], off offset:-512
	global_load_dword v64, v[38:39], off offset:-960
	global_load_dword v98, v[38:39], off
	global_load_dword v65, v[38:39], off offset:-448
	global_load_dword v101, v[38:39], off offset:-384
	global_load_dword v103, v[38:39], off offset:-320
	global_load_dword v105, v[38:39], off offset:-256
	global_load_dword v99, v[38:39], off offset:512
	global_load_dword v106, v[38:39], off offset:64
	global_load_dword v108, v[38:39], off offset:128
	global_load_dword v110, v[38:39], off offset:192
	global_load_dword v112, v[38:39], off offset:256
	global_load_dword v114, v[38:39], off offset:320
	global_load_dword v107, v[38:39], off offset:576
	global_load_dword v109, v[38:39], off offset:640
	global_load_dword v111, v[38:39], off offset:704
	global_load_dword v113, v[38:39], off offset:768
	global_load_dword v115, v[38:39], off offset:832
	global_load_dword v117, v[38:39], off offset:896
	global_load_dword v100, v[38:39], off offset:-896
	global_load_dword v102, v[38:39], off offset:-832
	global_load_dword v104, v[38:39], off offset:-768
	global_load_dword v118, v[38:39], off offset:-704
	global_load_dword v120, v[38:39], off offset:-640
	global_load_dword v122, v[38:39], off offset:-576
	global_load_dword v119, v[38:39], off offset:-192
	global_load_dword v121, v[38:39], off offset:-128
	global_load_dword v123, v[38:39], off offset:-64
	global_load_dword v116, v[38:39], off offset:384
	global_load_dword v124, v[38:39], off offset:448
	global_load_dword v125, v[38:39], off offset:960
	v_lshl_add_u64 v[34:35], v[34:35], 0, s[10:11]
	v_lshl_add_u64 v[36:37], v[36:37], 0, s[94:95]
	v_lshl_add_u64 v[38:39], v[38:39], 0, s[94:95]
	s_waitcnt vmcnt(33)
	v_pk_fma_f32 v[2:3], v[2:3], v[196:197], v[200:201]
	v_pk_fma_f32 v[6:7], v[6:7], v[196:197], v[202:203]
	v_pk_fma_f32 v[4:5], v[4:5], v[198:199], v[204:205]
	v_pk_fma_f32 v[8:9], v[8:9], v[198:199], v[212:213]
	v_pk_fma_f32 v[12:13], v[12:13], v[198:199], v[214:215]
	v_pk_fma_f32 v[16:17], v[16:17], v[198:199], v[216:217]
	v_pk_fma_f32 v[20:21], v[20:21], v[198:199], v[218:219]
	v_pk_fma_f32 v[24:25], v[24:25], v[198:199], v[220:221]
	v_pk_fma_f32 v[10:11], v[10:11], v[196:197], v[206:207]
	v_pk_fma_f32 v[14:15], v[14:15], v[196:197], v[208:209]
	v_pk_fma_f32 v[18:19], v[18:19], v[196:197], v[210:211]
	v_pk_fma_f32 v[22:23], v[22:23], v[196:197], v[224:225]
	v_pk_fma_f32 v[26:27], v[26:27], v[196:197], v[226:227]
	v_pk_fma_f32 v[30:31], v[30:31], v[196:197], v[228:229]
	v_pk_fma_f32 v[28:29], v[28:29], v[198:199], v[222:223]
	v_pk_fma_f32 v[32:33], v[32:33], v[198:199], v[230:231]
	s_waitcnt vmcnt(0)
	v_pk_fma_f32 v[2:3], v[2:3], v[58:59], v[62:63]
	v_pk_fma_f32 v[6:7], v[6:7], v[58:59], v[64:65]
	v_pk_fma_f32 v[4:5], v[4:5], v[60:61], v[98:99]
	v_pk_fma_f32 v[8:9], v[8:9], v[60:61], v[106:107]
	v_pk_fma_f32 v[12:13], v[12:13], v[60:61], v[108:109]
	v_pk_fma_f32 v[16:17], v[16:17], v[60:61], v[110:111]
	v_pk_fma_f32 v[20:21], v[20:21], v[60:61], v[112:113]
	v_pk_fma_f32 v[24:25], v[24:25], v[60:61], v[114:115]
	v_pk_fma_f32 v[10:11], v[10:11], v[58:59], v[100:101]
	v_pk_fma_f32 v[14:15], v[14:15], v[58:59], v[102:103]
	v_pk_fma_f32 v[18:19], v[18:19], v[58:59], v[104:105]
	v_pk_fma_f32 v[22:23], v[22:23], v[58:59], v[118:119]
	v_pk_fma_f32 v[26:27], v[26:27], v[58:59], v[120:121]
	v_pk_fma_f32 v[30:31], v[30:31], v[58:59], v[122:123]
	v_pk_fma_f32 v[28:29], v[28:29], v[60:61], v[116:117]
	v_pk_fma_f32 v[32:33], v[32:33], v[60:61], v[124:125]
	s_branch .Lhgu_done
.Lhgu_lastB:
	s_waitcnt vmcnt(0)
	v_pk_fma_f32 v[2:3], v[2:3], v[196:197], v[200:201]
	v_pk_fma_f32 v[6:7], v[6:7], v[196:197], v[202:203]
	v_pk_fma_f32 v[4:5], v[4:5], v[198:199], v[204:205]
	v_pk_fma_f32 v[8:9], v[8:9], v[198:199], v[212:213]
	v_pk_fma_f32 v[12:13], v[12:13], v[198:199], v[214:215]
	v_pk_fma_f32 v[16:17], v[16:17], v[198:199], v[216:217]
	v_pk_fma_f32 v[20:21], v[20:21], v[198:199], v[218:219]
	v_pk_fma_f32 v[24:25], v[24:25], v[198:199], v[220:221]
	v_pk_fma_f32 v[10:11], v[10:11], v[196:197], v[206:207]
	v_pk_fma_f32 v[14:15], v[14:15], v[196:197], v[208:209]
	v_pk_fma_f32 v[18:19], v[18:19], v[196:197], v[210:211]
	v_pk_fma_f32 v[22:23], v[22:23], v[196:197], v[224:225]
	v_pk_fma_f32 v[26:27], v[26:27], v[196:197], v[226:227]
	v_pk_fma_f32 v[30:31], v[30:31], v[196:197], v[228:229]
	v_pk_fma_f32 v[28:29], v[28:29], v[198:199], v[222:223]
	v_pk_fma_f32 v[32:33], v[32:33], v[198:199], v[230:231]
	s_branch .Lhgu_done
.Lhgu_lastA:
	s_waitcnt vmcnt(0)
	v_pk_fma_f32 v[2:3], v[2:3], v[58:59], v[62:63]
	v_pk_fma_f32 v[6:7], v[6:7], v[58:59], v[64:65]
	v_pk_fma_f32 v[4:5], v[4:5], v[60:61], v[98:99]
	v_pk_fma_f32 v[8:9], v[8:9], v[60:61], v[106:107]
	v_pk_fma_f32 v[12:13], v[12:13], v[60:61], v[108:109]
	v_pk_fma_f32 v[16:17], v[16:17], v[60:61], v[110:111]
	v_pk_fma_f32 v[20:21], v[20:21], v[60:61], v[112:113]
	v_pk_fma_f32 v[24:25], v[24:25], v[60:61], v[114:115]
	v_pk_fma_f32 v[10:11], v[10:11], v[58:59], v[100:101]
	v_pk_fma_f32 v[14:15], v[14:15], v[58:59], v[102:103]
	v_pk_fma_f32 v[18:19], v[18:19], v[58:59], v[104:105]
	v_pk_fma_f32 v[22:23], v[22:23], v[58:59], v[118:119]
	v_pk_fma_f32 v[26:27], v[26:27], v[58:59], v[120:121]
	v_pk_fma_f32 v[30:31], v[30:31], v[58:59], v[122:123]
	v_pk_fma_f32 v[28:29], v[28:29], v[60:61], v[116:117]
	v_pk_fma_f32 v[32:33], v[32:33], v[60:61], v[124:125]
.Lhgu_done:
	s_mov_b32 s4, 0
	s_mov_b64 s[38:39], 0
